# NSA selected branch: skip 64-key tiles no query of the 32-query block selected (union mask, exact zero contributions)
# speedup vs baseline: 1.0555x; 1.0555x over previous
; __device__ void nsa_item(const Params& P, int l, int item, char* smem) {
;     ...
;       AttAcc A;
; #pragma unroll
;       for (int i = 0; i < 16; ++i) { A.o0[i] = 0.f; A.o1[i] = 0.f; }
;       A.m = -1e30f; A.l = 0.f;
;       const bf16_t* Kg = Hb + (br == 0 ? 1792 : 1920) + g * 64;
;       const bf16_t* VTg = (br == 0 ? P.VsT : P.VwT) + (size_t)((b * 2 + g) * 64) * 4096;
;       const int khi = t0 & ~63;
;       const int klo = (br == 0) ? 0 : (((t0 - 512 > 0) ? (t0 - 512) : 0) & ~63);
;       const int ntile = ((khi - klo) >> 6) + 1;
;       const int wlim = (br == 0) ? (1 << 30) : 512;
;       const int srow = tid >> 3, sc8 = (tid & 7) * 8;
;       const int koff = kperm(srow) * 72 + sc8, voff = 4608 + srow * 72 + sc8;
;       const bf16_t* kgp = Kg + (size_t)srow * HS + sc8;
;       const bf16_t* vgp = VTg + (size_t)srow * 4096 + sc8;
;       uint4 rk0, rk1, rv0, rv1;
;       rk0 = *(const uint4*)(kgp + (size_t)khi * HS); rk1 = *(const uint4*)(kgp + (size_t)(khi + 32) * HS);
;       rv0 = *(const uint4*)(vgp + khi); rv1 = *(const uint4*)(vgp + (size_t)32 * 4096 + khi);
;       *(uint4*)(kvs + koff) = rk0; *(uint4*)(kvs + koff + 32 * 72) = rk1;
;       *(uint4*)(kvs + voff) = rv0; *(uint4*)(kvs + voff + 32 * 72) = rv1;
;       __syncthreads();
; #pragma unroll 1
;       for (int i = 0; i < ntile; ++i) {
;         const int kb = khi - 64 * i;
;         const bool more = (i + 1 < ntile);
;         if (more) {
;           rk0 = *(const uint4*)(kgp + (size_t)(kb - 64) * HS); rk1 = *(const uint4*)(kgp + (size_t)(kb - 32) * HS);
;           rv0 = *(const uint4*)(vgp + kb - 64); rv1 = *(const uint4*)(vgp + (size_t)32 * 4096 + kb - 64);
;         }
;         const bf16_t* buf = kvs + (i & 1) * 9216;
;         f32x16 s0, s1;
; #pragma unroll
;         for (int e = 0; e < 16; ++e) { s0[e] = 0.f; s1[e] = 0.f; }
;         {
;           const bf16_t* kl = buf + q * 72 + hk * 8;
; #pragma unroll
;           for (int ks = 0; ks < 4; ++ks) {
;             s0 = mfma32(*(const bf16x8*)(kl + ks * 16), qf[ks], s0);
;             s1 = mfma32(*(const bf16x8*)(kl + 32 * 72 + ks * 16), qf[ks], s1);
;           }
;         }
;         float lane_bias = 0.f;
;         if (br == 0) { const bool selj = (selmask >> (kb >> 6)) & 1ull; lane_bias = selj ? 0.f : 1e30f; }
;         const bool masked = (kb + 63 > t0) || (br == 1 && kb <= t0 - 481);
.LBB0_179:
	s_and_b64 s[46:47], s[42:43], exec
	s_movk_i32 s2, 0x780
	s_cselect_b32 s46, s82, s24
	s_cselect_b32 s2, 0x700, s2
	s_cselect_b32 s39, s83, s25
	s_add_u32 s48, s46, s0
	s_addc_u32 s49, s39, s1
	s_and_b64 s[60:61], s[42:43], exec
	s_cselect_b32 s47, 0, s64
	s_lshl_b32 s2, s2, 1
	v_lshl_add_u64 v[0:1], v[102:103], 0, s[2:3]
	v_lshl_add_u64 v[2:3], s[48:49], 0, v[104:105]
	v_lshl_add_u64 v[2:3], v[2:3], 0, v[176:177]
	v_lshl_add_u64 v[4:5], v[0:1], 0, s[52:53]
	v_lshl_add_u64 v[0:1], s[54:55], 1, v[0:1]
	s_mov_b32 s57, s3
	global_load_dwordx4 v[80:83], v[4:5], off
	global_load_dwordx4 v[84:87], v[0:1], off
	v_lshl_add_u64 v[0:1], v[2:3], 0, s[56:57]
	v_add_co_u32_e32 v2, vcc, 0x40000, v0
	s_sub_i32 s47, s50, s47
	s_nop 0
	v_addc_co_u32_e32 v3, vcc, 0, v1, vcc
	global_load_dwordx4 v[88:91], v[0:1], off
	global_load_dwordx4 v[92:95], v[2:3], off
	s_ashr_i32 s57, s47, 6
	v_mov_b32_e32 v15, 0
	v_mov_b32_e32 v14, 0
	v_mov_b32_e32 v13, 0
	v_mov_b32_e32 v12, 0
	v_mov_b32_e32 v11, 0
	v_mov_b32_e32 v10, 0
	v_mov_b32_e32 v9, 0
	v_mov_b32_e32 v8, 0
	v_mov_b32_e32 v7, 0
	v_mov_b32_e32 v6, 0
	v_mov_b32_e32 v5, 0
	v_mov_b32_e32 v4, 0
	v_mov_b32_e32 v3, 0
	v_mov_b32_e32 v2, 0
	v_mov_b32_e32 v1, 0
	v_mov_b32_e32 v0, 0
	v_mov_b32_e32 v31, 0
	v_mov_b32_e32 v30, 0
	v_mov_b32_e32 v29, 0
	v_mov_b32_e32 v28, 0
	v_mov_b32_e32 v27, 0
	v_mov_b32_e32 v26, 0
	v_mov_b32_e32 v25, 0
	v_mov_b32_e32 v24, 0
	v_mov_b32_e32 v23, 0
	v_mov_b32_e32 v22, 0
	v_mov_b32_e32 v21, 0
	v_mov_b32_e32 v20, 0
	v_mov_b32_e32 v19, 0
	v_mov_b32_e32 v18, 0
	v_mov_b32_e32 v17, 0
	v_mov_b32_e32 v16, 0
	s_cmp_lt_i32 s57, 0
	v_mov_b32_e32 v156, 0
	s_waitcnt vmcnt(3)
	ds_write_b128 v152, v[80:83] offset:34816
	s_waitcnt vmcnt(2)
	ds_write_b128 v152, v[84:87] offset:39424
	s_waitcnt vmcnt(1)
	ds_write_b128 v107, v[88:91] offset:44032
	s_waitcnt vmcnt(0)
	ds_write_b128 v107, v[92:95] offset:48640
	s_waitcnt lgkmcnt(0)
	s_barrier
	s_cbranch_scc1 .LBB0_190
	s_and_b64 s[48:49], s[42:43], exec
	s_cselect_b32 s60, 2.0, 0x200
	s_add_i32 s62, s57, 1
	s_add_u32 s46, s46, s4
	v_mov_b32_e32 v14, v177
	v_mov_b32_e32 v15, v177
	s_addc_u32 s47, s39, 0
	v_mov_b32_e32 v0, v177
	v_mov_b32_e32 v1, v177
	v_mov_b32_e32 v2, v177
	v_mov_b32_e32 v3, v177
	v_mov_b32_e32 v4, v177
	v_mov_b32_e32 v5, v177
	v_mov_b32_e32 v6, v177
	v_mov_b32_e32 v7, v177
	v_mov_b32_e32 v8, v177
	v_mov_b32_e32 v9, v177
	v_mov_b32_e32 v10, v177
	v_mov_b32_e32 v11, v177
	v_mov_b32_e32 v12, v177
	v_mov_b32_e32 v13, v177
	v_mov_b64_e32 v[30:31], v[14:15]
	s_mov_b32 s61, s60
	v_lshl_add_u64 v[112:113], s[46:47], 0, v[108:109]
	v_lshl_add_u64 v[114:115], v[110:111], 0, s[2:3]
	v_mov_b32_e32 v32, v96
	v_mov_b32_e32 v33, v97
	s_nop 1
	v_or_b32_dpp v32, v32, v32 row_shr:1 row_mask:0xf bank_mask:0xf bound_ctrl:1
	v_or_b32_dpp v33, v33, v33 row_shr:1 row_mask:0xf bank_mask:0xf bound_ctrl:1
	s_nop 0
	v_or_b32_dpp v32, v32, v32 row_shr:2 row_mask:0xf bank_mask:0xf bound_ctrl:1
	v_or_b32_dpp v33, v33, v33 row_shr:2 row_mask:0xf bank_mask:0xf bound_ctrl:1
	s_nop 0
	v_or_b32_dpp v32, v32, v32 row_shr:4 row_mask:0xf bank_mask:0xf bound_ctrl:1
	v_or_b32_dpp v33, v33, v33 row_shr:4 row_mask:0xf bank_mask:0xf bound_ctrl:1
	s_nop 0
	v_or_b32_dpp v32, v32, v32 row_shr:8 row_mask:0xf bank_mask:0xf bound_ctrl:1
	v_or_b32_dpp v33, v33, v33 row_shr:8 row_mask:0xf bank_mask:0xf bound_ctrl:1
	s_nop 0
	v_or_b32_dpp v32, v32, v32 row_bcast:15 row_mask:0xa bank_mask:0xf
	v_or_b32_dpp v33, v33, v33 row_bcast:15 row_mask:0xa bank_mask:0xf
	s_nop 0
	v_or_b32_dpp v32, v32, v32 row_bcast:31 row_mask:0xc bank_mask:0xf
	v_or_b32_dpp v33, v33, v33 row_bcast:31 row_mask:0xc bank_mask:0xf
	s_nop 1
	v_readlane_b32 s46, v32, 63
	v_readlane_b32 s47, v33, 63
	s_lshr_b32 s39, s38, 6
	s_and_b64 s[48:49], s[42:43], exec
	s_cbranch_scc1 .Lnsa_skip_m0
	s_lshr_b32 s48, s64, 6
	s_mov_b64 s[46:47], -1
	s_lshl_b64 s[46:47], s[46:47], s48
.Lnsa_skip_m0:
	s_mov_b64 s[48:49], -2
	s_lshl_b64 s[48:49], s[48:49], s39
	s_andn2_b64 s[46:47], s[46:47], s[48:49]
	s_bitset1_b64 s[46:47], s39
	s_bcnt1_i32_b64 s62, s[46:47]
	s_add_i32 s57, s62, -1
	s_bitset0_b64 s[46:47], s39
	s_flbit_i32_b64 s48, s[46:47]
	s_sub_i32 s48, 63, s48
	s_add_i32 s49, s39, -1
	s_cmp_lg_u64 s[46:47], 0
	s_cselect_b32 s48, s48, s49
	s_bitset0_b64 s[46:47], s48
	s_sub_i32 s49, s39, s48
	s_add_i32 s49, s49, -1
	v_writelane_b32 v253, s46, 0
	s_nop 1
	v_writelane_b32 v253, s47, 1
	v_writelane_b32 v253, s48, 2
	s_mul_i32 s46, s49, 0xfffbf400
	s_ashr_i32 s47, s46, 31
	v_lshl_add_u64 v[114:115], v[114:115], 0, s[46:47]
	s_lshl_b32 s46, s49, 7
	s_sub_i32 s46, 0, s46
	s_ashr_i32 s47, s46, 31
	v_lshl_add_u64 v[112:113], v[112:113], 0, s[46:47]
	s_mov_b32 s2, 0
	v_mov_b32_e32 v156, 0
	v_mov_b32_e32 v158, 0xf149f2ca
	s_mov_b32 s63, s38
	v_mov_b32_e32 v157, v154
	v_mov_b64_e32 v[28:29], v[12:13]
	v_mov_b64_e32 v[26:27], v[10:11]
	v_mov_b64_e32 v[24:25], v[8:9]
	v_mov_b64_e32 v[22:23], v[6:7]
	v_mov_b64_e32 v[20:21], v[4:5]
	v_mov_b64_e32 v[18:19], v[2:3]
	v_mov_b64_e32 v[16:17], v[0:1]
	s_branch .LBB0_182
.LBB0_181:
	v_add_f32_e32 v46, 0, v46
	v_add_f32_e32 v46, v47, v46
	v_add_f32_e32 v46, v60, v46
	v_add_f32_e32 v46, v61, v46
	v_add_f32_e32 v46, v52, v46
	v_add_f32_e32 v46, v53, v46
	v_add_f32_e32 v46, v54, v46
	v_add_f32_e32 v46, v55, v46
	v_add_f32_e32 v46, v56, v46
	v_add_f32_e32 v46, v57, v46
	v_add_f32_e32 v46, v58, v46
	v_add_f32_e32 v46, v59, v46
	v_add_f32_e32 v42, v42, v46
	v_add_f32_e32 v42, v43, v42
	v_add_f32_e32 v42, v44, v42
	v_add_f32_e32 v42, v45, v42
	v_add_f32_e32 v42, v62, v42
	v_add_f32_e32 v42, v63, v42
	v_add_f32_e32 v42, v50, v42
	v_add_f32_e32 v42, v51, v42
	v_add_f32_e32 v42, v48, v42
	v_add_f32_e32 v42, v49, v42
	v_add_f32_e32 v34, v34, v42
	v_add_f32_e32 v34, v35, v34
	v_add_f32_e32 v34, v36, v34
	v_add_f32_e32 v34, v37, v34
	v_add_f32_e32 v34, v38, v34
	v_add_f32_e32 v34, v39, v34
	v_add_f32_e32 v34, v40, v34
	v_add_f32_e32 v34, v41, v34
	v_add_f32_e32 v32, v32, v34
	v_add_f32_e32 v32, v33, v32
	v_add_f32_e32 v156, v156, v32
	v_readlane_b32 s46, v253, 0
	v_readlane_b32 s47, v253, 1
	v_readlane_b32 s48, v253, 2
	s_lshl_b32 s49, s48, 6
	s_add_i32 s49, s49, 63
	s_sub_i32 s39, s63, s49
	s_mov_b32 s63, s49
	v_add_u32_e32 v157, s39, v157
	s_flbit_i32_b64 s39, s[46:47]
	s_sub_i32 s39, 63, s39
	s_cmp_lg_u64 s[46:47], 0
	s_cselect_b32 s39, s39, s48
	s_bitset0_b64 s[46:47], s39
	s_sub_i32 s49, s48, s39
	v_writelane_b32 v253, s46, 0
	s_nop 1
	v_writelane_b32 v253, s47, 1
	v_writelane_b32 v253, s39, 2
	s_mul_i32 s46, s49, 0xfffbf400
	s_ashr_i32 s47, s46, 31
	v_lshl_add_u64 v[114:115], v[114:115], 0, s[46:47]
	s_lshl_b32 s46, s49, 7
	s_sub_i32 s46, 0, s46
	s_ashr_i32 s47, s46, 31
	v_lshl_add_u64 v[112:113], v[112:113], 0, s[46:47]
	s_cmp_eq_u32 s62, s2
	s_waitcnt lgkmcnt(0)
	s_barrier
	s_cbranch_scc1 .LBB0_190

; __global__ void __launch_bounds__(256, 2) mega_kernel(Params P, int ph_lo, int ph_hi) {
;   __shared__ __attribute__((aligned(16))) char smem[73728];
	.amdhsa_kernel _Z11mega_kernel6Paramsii
		.amdhsa_group_segment_fixed_size 73744
		.amdhsa_private_segment_fixed_size 0
		.amdhsa_kernarg_size 728
		.amdhsa_user_sgpr_count 2
		.amdhsa_user_sgpr_dispatch_ptr 0
		.amdhsa_user_sgpr_queue_ptr 0
		.amdhsa_user_sgpr_kernarg_segment_ptr 1
		.amdhsa_user_sgpr_dispatch_id 0
		.amdhsa_user_sgpr_kernarg_preload_length 0
		.amdhsa_user_sgpr_kernarg_preload_offset 0
		.amdhsa_user_sgpr_private_segment_size 0
		.amdhsa_uses_dynamic_stack 0
		.amdhsa_enable_private_segment 0
		.amdhsa_system_sgpr_workgroup_id_x 1
		.amdhsa_system_sgpr_workgroup_id_y 0
		.amdhsa_system_sgpr_workgroup_id_z 0
		.amdhsa_system_sgpr_workgroup_info 0
		.amdhsa_system_vgpr_workitem_id 2
		.amdhsa_next_free_vgpr 254
		.amdhsa_next_free_sgpr 100
		.amdhsa_accum_offset 256
		.amdhsa_reserve_vcc 1
		.amdhsa_float_round_mode_32 0
		.amdhsa_float_round_mode_16_64 0
		.amdhsa_float_denorm_mode_32 3
		.amdhsa_float_denorm_mode_16_64 3
		.amdhsa_dx10_clamp 1
		.amdhsa_ieee_mode 1
		.amdhsa_fp16_overflow 0
		.amdhsa_tg_split 0
		.amdhsa_exception_fp_ieee_invalid_op 0
		.amdhsa_exception_fp_denorm_src 0
		.amdhsa_exception_fp_ieee_div_zero 0
		.amdhsa_exception_fp_ieee_overflow 0
		.amdhsa_exception_fp_ieee_underflow 0
		.amdhsa_exception_fp_ieee_inexact 0
		.amdhsa_exception_int_div_zero 0
	.end_amdhsa_kernel

; __global__ void __launch_bounds__(256, 2) mega_kernel(Params P, int ph_lo, int ph_hi) {
;   __shared__ __attribute__((aligned(16))) char smem[73728];
amdhsa.kernels:
  - .agpr_count:     0
    .args:
      - .offset:         0
        .size:           464
        .value_kind:     by_value
      - .offset:         464
        .size:           4
        .value_kind:     by_value
      - .offset:         468
        .size:           4
        .value_kind:     by_value
      - .offset:         472
        .size:           4
        .value_kind:     hidden_block_count_x
      - .offset:         476
        .size:           4
        .value_kind:     hidden_block_count_y
      - .offset:         480
        .size:           4
        .value_kind:     hidden_block_count_z
      - .offset:         484
        .size:           2
        .value_kind:     hidden_group_size_x
      - .offset:         486
        .size:           2
        .value_kind:     hidden_group_size_y
      - .offset:         488
        .size:           2
        .value_kind:     hidden_group_size_z
      - .offset:         490
        .size:           2
        .value_kind:     hidden_remainder_x
      - .offset:         492
        .size:           2
        .value_kind:     hidden_remainder_y
      - .offset:         494
        .size:           2
        .value_kind:     hidden_remainder_z
      - .offset:         512
        .size:           8
        .value_kind:     hidden_global_offset_x
      - .offset:         520
        .size:           8
        .value_kind:     hidden_global_offset_y
      - .offset:         528
        .size:           8
        .value_kind:     hidden_global_offset_z
      - .offset:         536
        .size:           2
        .value_kind:     hidden_grid_dims
      - .offset:         560
        .size:           8
        .value_kind:     hidden_multigrid_sync_arg
    .group_segment_fixed_size: 73744
    .kernarg_segment_align: 8
    .kernarg_segment_size: 728
    .language:       OpenCL C
    .language_version:
      - 2
      - 0
    .max_flat_workgroup_size: 256
    .name:           _Z11mega_kernel6Paramsii
    .private_segment_fixed_size: 0
    .sgpr_count:     106
    .sgpr_spill_count: 309
    .symbol:         _Z11mega_kernel6Paramsii.kd
    .uniform_work_group_size: 1
    .uses_dynamic_stack: false
    .vgpr_count:     254
    .vgpr_spill_count: 0
    .wavefront_size: 64
